# G4 K-loop: next K-step LDS fragment reads interleaved one per MFMA gap (register double buffer), as in G5/G6
# speedup vs baseline: 1.0335x; 1.0017x over previous
.LBB0_271:
	s_or_b64 exec, exec, s[6:7]
	s_add_i32 s6, s13, 0
	v_add_u32_e32 v131, s6, v178
	v_add_u32_e32 v130, s6, v180
	v_add_u32_e32 v133, v131, v181
	v_add_u32_e32 v230, v130, v181
	ds_read_b128 v[186:189], v133
	ds_read_b128 v[190:193], v133 offset:4096
	ds_read_b128 v[194:197], v133 offset:8192
	ds_read_b128 v[202:205], v230 offset:32768
	ds_read_b128 v[206:209], v230 offset:36864
	v_add_u32_e32 v133, v131, v179
	v_add_u32_e32 v230, v130, v179
	s_setprio 1
	s_waitcnt lgkmcnt(0)
	v_mfma_f32_32x32x16_bf16 v[112:127], v[186:189], v[202:205], v[112:127]
	ds_read_b128 v[210:213], v133
	v_mfma_f32_32x32x16_bf16 v[96:111], v[186:189], v[206:209], v[96:111]
	ds_read_b128 v[214:217], v133 offset:4096
	v_mfma_f32_32x32x16_bf16 v[80:95], v[190:193], v[202:205], v[80:95]
	ds_read_b128 v[218:221], v133 offset:8192
	v_mfma_f32_32x32x16_bf16 v[64:79], v[190:193], v[206:209], v[64:79]
	ds_read_b128 v[198:201], v230 offset:32768
	v_mfma_f32_32x32x16_bf16 v[48:63], v[194:197], v[202:205], v[48:63]
	ds_read_b128 v[240:243], v230 offset:36864
	v_mfma_f32_32x32x16_bf16 v[32:47], v[194:197], v[206:209], v[32:47]
	s_setprio 0
	v_add_u32_e32 v133, v131, v169
	v_add_u32_e32 v230, v130, v169
	s_setprio 1
	s_waitcnt lgkmcnt(0)
	v_mfma_f32_32x32x16_bf16 v[112:127], v[210:213], v[198:201], v[112:127]
	ds_read_b128 v[186:189], v133
	v_mfma_f32_32x32x16_bf16 v[96:111], v[210:213], v[240:243], v[96:111]
	ds_read_b128 v[190:193], v133 offset:4096
	v_mfma_f32_32x32x16_bf16 v[80:95], v[214:217], v[198:201], v[80:95]
	ds_read_b128 v[194:197], v133 offset:8192
	v_mfma_f32_32x32x16_bf16 v[64:79], v[214:217], v[240:243], v[64:79]
	ds_read_b128 v[202:205], v230 offset:32768
	v_mfma_f32_32x32x16_bf16 v[48:63], v[218:221], v[198:201], v[48:63]
	ds_read_b128 v[206:209], v230 offset:36864
	v_mfma_f32_32x32x16_bf16 v[32:47], v[218:221], v[240:243], v[32:47]
	s_setprio 0
	s_and_saveexec_b64 s[6:7], s[0:1]
	s_cbranch_execz .LBB0_273
	s_xor_b32 s13, s13, 0x10000
	s_add_i32 s13, s13, 0
	v_add_u32_e32 v133, s13, v177
	v_add_u32_e32 v222, s13, v176
	v_readfirstlane_b32 s14, v133
	v_lshl_add_u64 v[228:229], v[150:151], 0, s[4:5]
	s_mov_b32 m0, s14
	v_readfirstlane_b32 s14, v222
	v_add_u32_e32 v223, s13, v175
	global_load_lds_dwordx4 v[228:229], off nt
	v_lshl_add_u64 v[228:229], v[152:153], 0, s[4:5]
	s_mov_b32 m0, s14
	v_readfirstlane_b32 s14, v223
	v_add_u32_e32 v227, s13, v174
	global_load_lds_dwordx4 v[228:229], off nt
	v_lshl_add_u64 v[228:229], v[154:155], 0, s[4:5]
	s_mov_b32 m0, s14
	v_readfirstlane_b32 s13, v227
	v_add_u32_e32 v133, 0x8000, v133
	global_load_lds_dwordx4 v[228:229], off nt
	v_readfirstlane_b32 s13, v133
	v_add_u32_e32 v133, 0x8000, v222
	v_lshl_add_u64 v[228:229], v[158:159], 0, s[4:5]
	s_mov_b32 m0, s13
	v_readfirstlane_b32 s13, v133
	v_add_u32_e32 v133, 0x8000, v223
	global_load_lds_dwordx4 v[228:229], off
	v_lshl_add_u64 v[228:229], v[160:161], 0, s[4:5]
	s_mov_b32 m0, s13
	v_readfirstlane_b32 s13, v133
	v_add_u32_e32 v133, 0x8000, v227
	global_load_lds_dwordx4 v[228:229], off
	v_lshl_add_u64 v[228:229], v[162:163], 0, s[4:5]
	s_mov_b32 m0, s13
	v_readfirstlane_b32 s13, v133
	global_load_lds_dwordx4 v[228:229], off
	v_lshl_add_u64 v[228:229], v[164:165], 0, s[4:5]
	s_mov_b32 m0, s13
	s_nop 0
	global_load_lds_dwordx4 v[228:229], off
.LBB0_273:
	s_or_b64 exec, exec, s[6:7]
	v_add_u32_e32 v133, v131, v168
	v_add_u32_e32 v230, v130, v168
	s_setprio 1
	s_waitcnt lgkmcnt(0)
	v_mfma_f32_32x32x16_bf16 v[112:127], v[186:189], v[202:205], v[112:127]
	ds_read_b128 v[210:213], v133
	v_mfma_f32_32x32x16_bf16 v[96:111], v[186:189], v[206:209], v[96:111]
	ds_read_b128 v[214:217], v133 offset:4096
	v_mfma_f32_32x32x16_bf16 v[80:95], v[190:193], v[202:205], v[80:95]
	ds_read_b128 v[218:221], v133 offset:8192
	v_mfma_f32_32x32x16_bf16 v[64:79], v[190:193], v[206:209], v[64:79]
	ds_read_b128 v[198:201], v230 offset:32768
	v_mfma_f32_32x32x16_bf16 v[48:63], v[194:197], v[202:205], v[48:63]
	ds_read_b128 v[240:243], v230 offset:36864
	v_mfma_f32_32x32x16_bf16 v[32:47], v[194:197], v[206:209], v[32:47]
	s_setprio 0
	s_setprio 1
	s_waitcnt lgkmcnt(0)
	v_mfma_f32_32x32x16_bf16 v[112:127], v[210:213], v[198:201], v[112:127]
	v_mfma_f32_32x32x16_bf16 v[96:111], v[210:213], v[240:243], v[96:111]
	v_mfma_f32_32x32x16_bf16 v[80:95], v[214:217], v[198:201], v[80:95]
	v_mfma_f32_32x32x16_bf16 v[64:79], v[214:217], v[240:243], v[64:79]
	v_mfma_f32_32x32x16_bf16 v[48:63], v[218:221], v[198:201], v[48:63]
	v_mfma_f32_32x32x16_bf16 v[32:47], v[218:221], v[240:243], v[32:47]
	s_setprio 0
	s_xor_b32 s6, s9, 1
	s_waitcnt vmcnt(0)
	s_add_u32 s4, s4, 0x80
	s_addc_u32 s5, s5, 0
	s_cmpk_lg_i32 s4, 0x780
	s_waitcnt vmcnt(0)
	s_barrier
	s_cbranch_scc1 .LBB0_269
	v_add_u32_e32 v237, s8, v128
	v_cmp_lt_i32_e64 s[36:37], 31, v237
	s_xor_b64 s[0:1], vcc, -1
	s_nor_b64 s[0:1], s[0:1], s[36:37]
	v_cndmask_b32_e64 v128, v237, v128, s[36:37]
	v_ashrrev_i32_e32 v130, 31, v128
	v_lshrrev_b32_e32 v130, 30, v130
	v_add_u32_e32 v130, v128, v130
	v_lshrrev_b32_e32 v131, 2, v130
	v_and_b32_e32 v130, 0xfffffc, v130
	v_sub_u32_e32 v130, v128, v130
	v_lshlrev_b32_e32 v128, 4, v132
	v_and_b32_e32 v128, 0x70, v128
	v_add_lshl_u32 v236, v131, v233, 8
	v_lshl_add_u64 v[136:137], s[44:45], 0, v[128:129]
	v_lshl_add_u64 v[134:135], s[46:47], 0, v[128:129]
	v_lshlrev_b32_e32 v238, 8, v130
	s_and_saveexec_b64 s[14:15], s[0:1]
	s_xor_b64 s[0:1], exec, s[14:15]
	s_cbranch_execz .LBB0_276
	s_lshl_b32 s4, s6, 16
	s_xor_b32 s5, s4, 0x10000
	v_add_u32_e32 v130, v236, v185
	s_add_i32 s5, s5, 0
	v_ashrrev_i32_e32 v131, 31, v130
	v_add_u32_e32 v132, v184, v236
	v_add_u32_e32 v128, s5, v177
	v_lshlrev_b64 v[130:131], 11, v[130:131]
	v_ashrrev_i32_e32 v133, 31, v132
	v_readfirstlane_b32 s7, v128
	v_add_u32_e32 v142, s5, v176
	v_lshl_add_u64 v[130:131], v[136:137], 0, v[130:131]
	v_lshlrev_b64 v[132:133], 11, v[132:133]
	s_mov_b32 m0, s7
	v_readfirstlane_b32 s7, v142
	v_lshl_add_u64 v[132:133], v[136:137], 0, v[132:133]
	v_add_u32_e32 v138, v183, v236
	global_load_lds_dwordx4 v[130:131], off
	s_mov_b32 m0, s7
	v_ashrrev_i32_e32 v139, 31, v138
	v_add_u32_e32 v140, v182, v236
	global_load_lds_dwordx4 v[132:133], off
	v_add_u32_e32 v132, s5, v175
	v_lshlrev_b64 v[138:139], 11, v[138:139]
	v_ashrrev_i32_e32 v141, 31, v140
	v_readfirstlane_b32 s7, v132
	v_add_u32_e32 v133, s5, v174
	v_add_u32_e32 v130, v238, v185
	v_lshl_add_u64 v[138:139], v[136:137], 0, v[138:139]
	v_lshlrev_b64 v[140:141], 11, v[140:141]
	s_mov_b32 m0, s7
	v_readfirstlane_b32 s5, v133
	v_ashrrev_i32_e32 v131, 31, v130
	v_add_u32_e32 v128, 0x8000, v128
	v_lshl_add_u64 v[140:141], v[136:137], 0, v[140:141]
	global_load_lds_dwordx4 v[138:139], off
	s_mov_b32 m0, s5
	v_lshlrev_b64 v[130:131], 11, v[130:131]
	v_readfirstlane_b32 s5, v128
	global_load_lds_dwordx4 v[140:141], off
	v_lshl_add_u64 v[130:131], v[134:135], 0, v[130:131]
	s_mov_b32 m0, s5
	v_add_u32_e32 v128, 0x8000, v142
	global_load_lds_dwordx4 v[130:131], off
	v_add_u32_e32 v130, v184, v238
	v_ashrrev_i32_e32 v131, 31, v130
	v_lshlrev_b64 v[130:131], 11, v[130:131]
	v_readfirstlane_b32 s5, v128
	v_lshl_add_u64 v[130:131], v[134:135], 0, v[130:131]
	s_mov_b32 m0, s5
	v_add_u32_e32 v128, 0x8000, v132
	global_load_lds_dwordx4 v[130:131], off
	v_add_u32_e32 v130, v183, v238
	v_ashrrev_i32_e32 v131, 31, v130
	v_lshlrev_b64 v[130:131], 11, v[130:131]
	v_readfirstlane_b32 s5, v128
	v_lshl_add_u64 v[130:131], v[134:135], 0, v[130:131]
	s_mov_b32 m0, s5
	v_add_u32_e32 v128, 0x8000, v133
	global_load_lds_dwordx4 v[130:131], off
	v_add_u32_e32 v130, v182, v238
	v_ashrrev_i32_e32 v131, 31, v130
	v_lshlrev_b64 v[130:131], 11, v[130:131]
	v_readfirstlane_b32 s5, v128
	v_lshl_add_u64 v[130:131], v[134:135], 0, v[130:131]
	s_mov_b32 m0, s5
	s_nop 0
	global_load_lds_dwordx4 v[130:131], off
